# idx scoring: 45 v_pk_fma_f32 in the tile loop (beside the MFMA blocks) split into scalar v_fma_f32 pairs; plus c11
# speedup vs baseline: 1.0180x; 1.0018x over previous
.LBB0_871:
	s_bitcmp1_b32 s12, 0
	s_cselect_b32 s0, 0x2400, 0
	v_add_u32_e32 v32, s0, v221
	ds_read_b128 v[48:51], v32
	ds_read_b128 v[200:203], v32 offset:32
	ds_read_b128 v[204:207], v32 offset:64
	ds_read_b128 v[208:211], v32 offset:96
	s_setprio 1
	s_waitcnt lgkmcnt(3)
	v_mfma_f32_32x32x16_bf16 v[32:47], v[64:67], v[48:51], 0
	v_mfma_f32_32x32x16_bf16 v[48:63], v[80:83], v[48:51], 0
	s_waitcnt lgkmcnt(2)
	v_mfma_f32_32x32x16_bf16 v[32:47], v[68:71], v[200:203], v[32:47]
	v_mfma_f32_32x32x16_bf16 v[48:63], v[84:87], v[200:203], v[48:63]
	s_waitcnt lgkmcnt(1)
	v_mfma_f32_32x32x16_bf16 v[32:47], v[72:75], v[204:207], v[32:47]
	v_mfma_f32_32x32x16_bf16 v[48:63], v[88:91], v[204:207], v[48:63]
	s_waitcnt lgkmcnt(0)
	v_mfma_f32_32x32x16_bf16 v[32:47], v[76:79], v[208:211], v[32:47]
	v_mfma_f32_32x32x16_bf16 v[48:63], v[92:95], v[208:211], v[48:63]
	s_setprio 0
	v_max_i32_e32 v201, 0, v1
	v_max_i32_e32 v200, 0, v0
	v_fma_f32 v200, v182, v200, 0
	v_fma_f32 v201, v183, v201, 0
	v_max_i32_e32 v203, 0, v3
	v_max_i32_e32 v202, 0, v2
	v_fma_f32 v200, v180, v202, v200
	v_fma_f32 v201, v181, v203, v201
	v_max_i32_e32 v203, 0, v5
	v_max_i32_e32 v202, 0, v4
	v_fma_f32 v200, v178, v202, v200
	v_fma_f32 v201, v179, v203, v201
	v_max_i32_e32 v203, 0, v7
	v_max_i32_e32 v202, 0, v6
	v_fma_f32 v200, v176, v202, v200
	v_fma_f32 v201, v177, v203, v201
	v_max_i32_e32 v203, 0, v9
	v_max_i32_e32 v202, 0, v8
	v_fma_f32 v200, v174, v202, v200
	v_fma_f32 v201, v175, v203, v201
	v_max_i32_e32 v203, 0, v11
	v_max_i32_e32 v202, 0, v10
	v_fma_f32 v200, v172, v202, v200
	v_fma_f32 v201, v173, v203, v201
	v_max_i32_e32 v203, 0, v13
	v_max_i32_e32 v202, 0, v12
	v_fma_f32 v200, v170, v202, v200
	v_fma_f32 v201, v171, v203, v201
	v_max_i32_e32 v203, 0, v15
	v_max_i32_e32 v202, 0, v14
	v_fma_f32 v200, v168, v202, v200
	v_fma_f32 v201, v169, v203, v201
	v_max_i32_e32 v203, 0, v17
	v_max_i32_e32 v202, 0, v16
	v_fma_f32 v202, v198, v202, 0
	v_fma_f32 v203, v199, v203, 0
	v_max_i32_e32 v205, 0, v19
	v_max_i32_e32 v204, 0, v18
	v_fma_f32 v202, v196, v204, v202
	v_fma_f32 v203, v197, v205, v203
	v_max_i32_e32 v205, 0, v21
	v_max_i32_e32 v204, 0, v20
	v_fma_f32 v202, v194, v204, v202
	v_fma_f32 v203, v195, v205, v203
	v_max_i32_e32 v205, 0, v23
	v_max_i32_e32 v204, 0, v22
	v_fma_f32 v202, v192, v204, v202
	v_fma_f32 v203, v193, v205, v203
	v_max_i32_e32 v205, 0, v25
	v_max_i32_e32 v204, 0, v24
	v_fma_f32 v202, v190, v204, v202
	v_fma_f32 v203, v191, v205, v203
	v_max_i32_e32 v205, 0, v27
	v_max_i32_e32 v204, 0, v26
	v_fma_f32 v202, v188, v204, v202
	v_fma_f32 v203, v189, v205, v203
	v_max_i32_e32 v205, 0, v29
	v_max_i32_e32 v204, 0, v28
	v_fma_f32 v202, v186, v204, v202
	v_fma_f32 v203, v187, v205, v203
	v_max_i32_e32 v205, 0, v31
	v_max_i32_e32 v204, 0, v30
	v_fma_f32 v202, v184, v204, v202
	v_fma_f32 v203, v185, v205, v203
	v_mov_b32_e32 v205, v200
	v_mov_b32_e32 v204, v202
	v_mov_b32_e32 v200, v203
	v_pk_add_f32 v[200:201], v[204:205], v[200:201]
	s_lshl_b32 s13, s12, 6
	v_not_b32_e32 v202, v201
	v_or_b32_e32 v203, 0x80000000, v201
	v_cmp_gt_i32_e32 vcc, 0, v201
	v_cmp_gt_i32_e64 s[0:1], 0, v200
	s_nop 0
	v_cndmask_b32_e32 v201, v203, v202, vcc
	v_and_b32_e32 v201, 0xffffc000, v201
	v_or3_b32 v201, v119, v201, s13
	v_cmp_gt_u32_e32 vcc, v201, v247
	s_cbranch_vccz .LBB0_959
	s_nop 0
	v_lshrrev_b64 v[202:203], v118, vcc
	s_and_saveexec_b64 s[2:3], vcc
	s_cbranch_execz .LBB0_874
	v_and_b32_e32 v204, v202, v222
	v_bcnt_u32_b32 v204, v204, 0
	v_lshlrev_b32_e32 v203, 2, v132
	v_lshlrev_b32_e32 v204, 2, v204
	v_add3_u32 v203, v223, v203, v204
	ds_write_b32 v203, v201

.LBB0_1052:
	v_fma_f32 v32, v140, v208, 0
	v_fma_f32 v33, v141, v209, 0
	v_fma_f32 v44, v142, v206, 0
	v_fma_f32 v45, v143, v207, 0
	v_fma_f32 v32, v144, v202, v32
	v_fma_f32 v33, v145, v203, v33
	v_fma_f32 v44, v146, v204, v44
	v_fma_f32 v45, v147, v205, v45
	v_fma_f32 v32, v148, v110, v32
	v_fma_f32 v33, v149, v111, v33
	v_fma_f32 v44, v150, v108, v44
	v_fma_f32 v45, v151, v109, v45
	v_fma_f32 v32, v136, v38, v32
	v_fma_f32 v33, v137, v39, v33
	v_fma_f32 v44, v138, v36, v44
	v_fma_f32 v45, v139, v37, v45
	v_fma_f32 v32, v152, v200, v32
	v_fma_f32 v33, v153, v201, v33
	v_fma_f32 v44, v154, v54, v44
	v_fma_f32 v45, v155, v55, v45
	v_fma_f32 v32, v156, v52, v32
	v_fma_f32 v33, v157, v53, v33
	v_fma_f32 v44, v158, v50, v44
	v_fma_f32 v45, v159, v51, v45
	v_fma_f32 v32, v160, v48, v32
	v_fma_f32 v33, v161, v49, v33
	v_fma_f32 v44, v162, v42, v44
	v_fma_f32 v45, v163, v43, v45
	v_fma_f32 v32, v164, v40, v32
	v_fma_f32 v33, v165, v41, v33
	v_fma_f32 v44, v166, v34, v44
	v_fma_f32 v45, v167, v35, v45
	s_nop 0
	v_pk_add_f32 v[32:33], v[32:33], v[44:45]
	s_nop 0
	v_and_b32_e32 v45, 0x7fffffff, v33
	v_and_b32_e32 v44, 0x7fffffff, v32
	v_xor_b32_e32 v46, -1, v33
	v_pk_add_f32 v[44:45], v[44:45], 0 neg_lo:[1,1] neg_hi:[1,1]
	v_cmp_gt_i32_e32 vcc, 0, v33
	v_xor_b32_e32 v47, -1, v32
	s_nop 0
	v_cndmask_b32_e32 v33, v45, v46, vcc
	v_cmp_gt_i32_e32 vcc, 0, v32
	s_nop 1
	v_cndmask_b32_e32 v32, v44, v47, vcc
	s_cbranch_execnz .LBB0_1051
.LBB0_1053:
	v_add3_u32 v0, s11, v219, v116
	ds_read_b128 v[16:19], v0
	ds_read_b128 v[44:47], v0 offset:32
	ds_read_b128 v[56:59], v0 offset:64
	ds_read_b128 v[60:63], v0 offset:96
	s_setprio 1
	s_waitcnt lgkmcnt(3)
	v_mfma_f32_32x32x16_bf16 v[0:15], v[64:67], v[16:19], 0
	v_mfma_f32_32x32x16_bf16 v[16:31], v[80:83], v[16:19], 0
	s_waitcnt lgkmcnt(2)
	v_mfma_f32_32x32x16_bf16 v[0:15], v[68:71], v[44:47], v[0:15]
	v_mfma_f32_32x32x16_bf16 v[16:31], v[84:87], v[44:47], v[16:31]
	s_waitcnt lgkmcnt(1)
	v_mfma_f32_32x32x16_bf16 v[0:15], v[72:75], v[56:59], v[0:15]
	v_mfma_f32_32x32x16_bf16 v[16:31], v[88:91], v[56:59], v[16:31]
	s_waitcnt lgkmcnt(0)
	v_mfma_f32_32x32x16_bf16 v[0:15], v[76:79], v[60:63], v[0:15]
	v_mfma_f32_32x32x16_bf16 v[16:31], v[92:95], v[60:63], v[16:31]
	s_setprio 0
	v_fma_f32 v32, v140, v208, 0
	v_fma_f32 v33, v141, v209, 0
	v_fma_f32 v44, v142, v206, 0
	v_fma_f32 v45, v143, v207, 0
	v_fma_f32 v32, v144, v202, v32
	v_fma_f32 v33, v145, v203, v33
	v_fma_f32 v44, v146, v204, v44
	v_fma_f32 v45, v147, v205, v45
	v_fma_f32 v32, v148, v110, v32
	v_fma_f32 v33, v149, v111, v33
	v_fma_f32 v44, v150, v108, v44
	v_fma_f32 v45, v151, v109, v45
	v_fma_f32 v32, v136, v38, v32
	v_fma_f32 v33, v137, v39, v33
	v_fma_f32 v36, v138, v36, v44
	v_fma_f32 v37, v139, v37, v45
	v_fma_f32 v32, v152, v200, v32
	v_fma_f32 v33, v153, v201, v33
	v_fma_f32 v36, v154, v54, v36
	v_fma_f32 v37, v155, v55, v37
	v_fma_f32 v32, v156, v52, v32
	v_fma_f32 v33, v157, v53, v33
	v_fma_f32 v36, v158, v50, v36
	v_fma_f32 v37, v159, v51, v37
	v_fma_f32 v32, v160, v48, v32
	v_fma_f32 v33, v161, v49, v33
	v_fma_f32 v36, v162, v42, v36
	v_fma_f32 v37, v163, v43, v37
	v_fma_f32 v32, v164, v40, v32
	v_fma_f32 v33, v165, v41, v33
	v_fma_f32 v34, v166, v34, v36
	v_fma_f32 v35, v167, v35, v37
	s_nop 0
	v_pk_add_f32 v[32:33], v[32:33], v[34:35]
	s_nop 0
	v_xor_b32_e32 v36, -1, v33
	v_and_b32_e32 v35, 0x7fffffff, v33
	v_and_b32_e32 v34, 0x7fffffff, v32
	v_xor_b32_e32 v37, -1, v32
	v_pk_add_f32 v[34:35], v[34:35], 0 neg_lo:[1,1] neg_hi:[1,1]
	v_cmp_gt_i32_e32 vcc, 0, v32
	v_cmp_gt_i32_e64 s[0:1], 0, v33
	s_nop 0
	v_cndmask_b32_e32 v32, v34, v37, vcc
	v_cndmask_b32_e64 v33, v35, v36, s[0:1]
	v_and_b32_e32 v32, 0xffffc000, v32
	v_or3_b32 v32, v220, v32, s13
	v_cmp_gt_u32_e32 vcc, v32, v247
	s_cbranch_vccz .LBB0_1141
